# a+b plus loop-head alignment pin: s_nop pads so the P3a, P3b, P4 and P7 K-loop heads sit at 0 mod 64 bytes like P1 and P5
# speedup vs baseline: 1.0046x; 1.0044x over previous
; template <class Epi, class Sched>
; __device__ __forceinline__ void gemm_phase_dual(PG8_LAS unsigned char* lds, const Gemm g  , const bf16_t* A0, const bf16_t* Bt0, int K0, const Sched& S, const Epi& E) {
;     ...
;     for (;;) {
;         const char* mA = (const char*)g.A + (size_t)cur.pm * tstep; const char* mB = (const char*)g.Bt + (size_t)cur.pn * tstep;
;         PG8_KLOOP(nt0, cA, cB, mA, mB)
;     ...
; #pragma unroll
;         for (int a = 0; a < 2; ++a)
; #pragma unroll
;             for (int b = 0; b < 2; ++b)
; #pragma unroll
;                 for (int m = 0; m < 4; ++m)
; #pragma unroll
;                     for (int n = 0; n < 2; ++n) acc[a][b][m][n] = (f32x4){0.f, 0.f, 0.f, 0.f};
;         cur = nxt; cA = nA; cB = nB; ++ui;
.LBB0_745:
	s_ashr_i32 s5, s4, 31
	s_lshl_b64 s[0:1], s[4:5], 21
	s_add_u32 s30, s51, s0
	s_addc_u32 s31, s52, s1
	s_ashr_i32 s21, s20, 31
	s_lshl_b64 s[34:35], s[20:21], 21
	s_add_u32 s78, s53, s34
	s_addc_u32 s79, s54, s35
	s_add_u32 s0, s29, s38
	s_addc_u32 s1, s42, s39
	s_add_u32 s5, s68, s40
	v_mov_b32_e32 v2, 0
	s_addc_u32 s21, s69, s41
	s_mov_b32 s33, -2
	v_mov_b32_e32 v3, v2
	v_mov_b32_e32 v4, v2
	v_mov_b32_e32 v5, v2
	v_mov_b32_e32 v6, v2
	v_mov_b32_e32 v7, v2
	v_mov_b32_e32 v8, v2
	v_mov_b32_e32 v9, v2
	v_mov_b32_e32 v14, v2
	v_mov_b32_e32 v15, v2
	v_mov_b32_e32 v16, v2
	v_mov_b32_e32 v17, v2
	v_mov_b32_e32 v22, v2
	v_mov_b32_e32 v23, v2
	v_mov_b32_e32 v24, v2
	v_mov_b32_e32 v25, v2
	v_mov_b32_e32 v54, v2
	v_mov_b32_e32 v55, v2
	v_mov_b32_e32 v56, v2
	v_mov_b32_e32 v57, v2
	v_mov_b32_e32 v66, v2
	v_mov_b32_e32 v67, v2
	v_mov_b32_e32 v68, v2
	v_mov_b32_e32 v69, v2
	v_mov_b32_e32 v86, v2
	v_mov_b32_e32 v87, v2
	v_mov_b32_e32 v88, v2
	v_mov_b32_e32 v89, v2
	v_mov_b32_e32 v94, v2
	v_mov_b32_e32 v95, v2
	v_mov_b32_e32 v96, v2
	v_mov_b32_e32 v97, v2
	v_mov_b32_e32 v10, v2
	v_mov_b32_e32 v11, v2
	v_mov_b32_e32 v12, v2
	v_mov_b32_e32 v13, v2
	v_mov_b32_e32 v18, v2
	v_mov_b32_e32 v19, v2
	v_mov_b32_e32 v20, v2
	v_mov_b32_e32 v21, v2
	v_mov_b32_e32 v38, v2
	v_mov_b32_e32 v39, v2
	v_mov_b32_e32 v40, v2
	v_mov_b32_e32 v41, v2
	v_mov_b32_e32 v42, v2
	v_mov_b32_e32 v43, v2
	v_mov_b32_e32 v44, v2
	v_mov_b32_e32 v45, v2
	v_mov_b32_e32 v70, v2
	v_mov_b32_e32 v71, v2
	v_mov_b32_e32 v72, v2
	v_mov_b32_e32 v73, v2
	v_mov_b32_e32 v74, v2
	v_mov_b32_e32 v75, v2
	v_mov_b32_e32 v76, v2
	v_mov_b32_e32 v77, v2
	v_mov_b32_e32 v98, v2
	v_mov_b32_e32 v99, v2
	v_mov_b32_e32 v100, v2
	v_mov_b32_e32 v101, v2
	v_mov_b32_e32 v102, v2
	v_mov_b32_e32 v103, v2
	v_mov_b32_e32 v104, v2
	v_mov_b32_e32 v105, v2
	v_mov_b32_e32 v126, v2
	v_mov_b32_e32 v127, v2
	v_mov_b32_e32 v128, v2
	v_mov_b32_e32 v129, v2
	v_mov_b32_e32 v122, v2
	v_mov_b32_e32 v123, v2
	v_mov_b32_e32 v124, v2
	v_mov_b32_e32 v125, v2
	v_mov_b32_e32 v106, v2
	v_mov_b32_e32 v107, v2
	v_mov_b32_e32 v108, v2
	v_mov_b32_e32 v109, v2
	v_mov_b32_e32 v110, v2
	v_mov_b32_e32 v111, v2
	v_mov_b32_e32 v112, v2
	v_mov_b32_e32 v113, v2
	v_mov_b32_e32 v82, v2
	v_mov_b32_e32 v83, v2
	v_mov_b32_e32 v84, v2
	v_mov_b32_e32 v85, v2
	v_mov_b32_e32 v58, v2
	v_mov_b32_e32 v59, v2
	v_mov_b32_e32 v60, v2
	v_mov_b32_e32 v61, v2
	v_mov_b32_e32 v50, v2
	v_mov_b32_e32 v51, v2
	v_mov_b32_e32 v52, v2
	v_mov_b32_e32 v53, v2
	v_mov_b32_e32 v26, v2
	v_mov_b32_e32 v27, v2
	v_mov_b32_e32 v28, v2
	v_mov_b32_e32 v29, v2
	v_mov_b32_e32 v114, v2
	v_mov_b32_e32 v115, v2
	v_mov_b32_e32 v116, v2
	v_mov_b32_e32 v117, v2
	v_mov_b32_e32 v130, v2
	v_mov_b32_e32 v131, v2
	v_mov_b32_e32 v132, v2
	v_mov_b32_e32 v133, v2
	v_mov_b32_e32 v90, v2
	v_mov_b32_e32 v91, v2
	v_mov_b32_e32 v92, v2
	v_mov_b32_e32 v93, v2
	v_mov_b32_e32 v78, v2
	v_mov_b32_e32 v79, v2
	v_mov_b32_e32 v80, v2
	v_mov_b32_e32 v81, v2
	v_mov_b32_e32 v62, v2
	v_mov_b32_e32 v63, v2
	v_mov_b32_e32 v64, v2
	v_mov_b32_e32 v65, v2
	v_mov_b32_e32 v46, v2
	v_mov_b32_e32 v47, v2
	v_mov_b32_e32 v48, v2
	v_mov_b32_e32 v49, v2
	v_mov_b32_e32 v30, v2
	v_mov_b32_e32 v31, v2
	v_mov_b32_e32 v32, v2
	v_mov_b32_e32 v33, v2
	v_mov_b32_e32 v34, v2
	v_mov_b32_e32 v35, v2
	v_mov_b32_e32 v36, v2
	v_mov_b32_e32 v37, v2
	s_nop 0
	s_nop 0

;     __device__ bool next(int i, Unit& u) const { if (i > 1) return false; const int xcd = c & 7, idx = c >> 3; u.pm = 16 * i + 4 * (xcd >> 1) + (idx & 3); u.pn = 8 * (xcd & 1) + (idx >> 2); return true; }
; template <class Epi, class Sched>
; __device__ __forceinline__ void gemm_phase_dual(PG8_LAS unsigned char* lds, const Gemm g  , const bf16_t* A0, const bf16_t* Bt0, int K0, const Sched& S, const Epi& E) {
;     ...
;         E.mid(acc, cur, wr, wc, fr, fq);
;         const bool has_next = S.next(ui + 1, nxt);
;         const char* nA = has_next ? (const char*)A0 + (size_t)nxt.pm * tstep : mA; const char* nB = has_next ? (const char*)Bt0 + (size_t)nxt.pn * tstep : mB;
;         PG8_KLOOP(nt1, mA, mB, nA, nB)
.LBB0_753:
	s_ashr_i32 s5, s4, 31
	s_lshl_b64 s[38:39], s[4:5], 21
	s_add_u32 s16, s29, s38
	s_addc_u32 s5, s42, s39
	s_and_b64 s[2:3], s[0:1], exec
	s_cselect_b32 s5, s5, s31
	s_cselect_b32 s33, s16, s30
	s_ashr_i32 s21, s20, 31
	s_lshl_b64 s[40:41], s[20:21], 21
	s_add_u32 s16, s43, s40
	s_addc_u32 s17, s44, s41
	s_and_b64 s[2:3], s[0:1], exec
	s_cselect_b32 s21, s17, s79
	s_cselect_b32 s36, s16, s78
	s_add_u32 s34, s70, s34
	s_addc_u32 s35, s71, s35
	s_mov_b32 s37, -2
	s_nop 0
	s_nop 0
	s_nop 0
	s_nop 0
	s_nop 0
	s_nop 0
	s_nop 0
	s_nop 0
	s_nop 0
	s_nop 0

;     __device__ bool next(int i, Unit& u) const { if (i > 1) return false; const int xcd = c & 7, idx = c >> 3; u.pm = 16 * i + 4 * (xcd >> 1) + (idx & 3); u.pn = 8 * (xcd & 1) + (idx >> 2); return true; }
; #define PG8_STAGE(bufoff, gbase, voff) do { const char* _gb = (const char*)(gbase); asm volatile("" : "+s"(_gb)); _Pragma("unroll") for (int _i = 0; _i < 2; ++_i) { asm volatile("" : "+v"((voff)[_i])); \
;         __builtin_amdgcn_global_load_lds((const unsigned*)(_gb + (voff)[_i]), (PG8_LAS unsigned*)(lds + (bufoff) + ldsw + _i * 8192), 16, 0, 0); } } while (0)
; #define PG8_LDA(dst, b, h) do { _Pragma("unroll") for (int m = 0; m < 4; ++m) _Pragma("unroll") for (int k = 0; k < 2; ++k) dst[m][k] = *(const PG8_LAS bf16x8*)(lds + PG8_SA(b, h) + aoff + m * 2048 + k * 1024); } while (0)
; #define PG8_LDB(dst, b, h) do { _Pragma("unroll") for (int n = 0; n < 2; ++n) _Pragma("unroll") for (int k = 0; k < 2; ++k) dst[n][k] = *(const PG8_LAS bf16x8*)(lds + PG8_SB(b, h) + boff + n * 2048 + k * 1024); } while (0)
; #define PG8_SCHED __builtin_amdgcn_sched_barrier(0)
; template <class Epi, class Sched, bool ALIGN_EPI = false, bool SP2 = false>
; __device__ __forceinline__ void gemm_phase(PG8_LAS unsigned char* lds, const Gemm g, const Sched& S, const Epi& E) {
;     ...
;         const bool has_next = S.next(ui + 1, nxt);
;         const char* nA = has_next ? (const char*)g.A + (size_t)nxt.pm * tstep : cA; const char* nB = has_next ? (const char*)g.Bt + (size_t)nxt.pn * tstep : cB;
;         for (int t = 0; t < nt; t += 2) {
;             const bool last = (t == nt - 2);
;             const char* a1 = cA + (size_t)(t + 1) * kstep;
;             const char* a2 = last ? nA : cA + (size_t)(t + 2) * kstep; const char* b2 = last ? nB : cB + (size_t)(t + 2) * kstep;
;             const char* a3 = a2 + kstep; const char* b3 = b2 + kstep;
;             if (last && has_next) S.a_ready(nxt);
;             if constexpr (SP2) {
;             PG8_LDB(B0, 0, 0); PG8_LDB(B1, 0, 1); PG8_SCHED; PG8_LDA(At, 0, 0); PG8_STAGE(PG8_SA(1, 1), a1 + hstep, voffA);
;     ...
; #pragma unroll
;         for (int a = 0; a < 2; ++a)
; #pragma unroll
;             for (int b = 0; b < 2; ++b)
; #pragma unroll
;                 for (int m = 0; m < 4; ++m)
; #pragma unroll
;                     for (int n = 0; n < 2; ++n) acc[a][b][m][n] = (f32x4){0.f, 0.f, 0.f, 0.f};
;         cur = nxt; cA = nA; cB = nB; ++ui;
.LBB0_832:
	s_ashr_i32 s55, s54, 31
	s_lshl_b64 s[24:25], s[54:55], 21
	s_add_u32 s56, s33, s24
	s_addc_u32 s57, s96, s25
	s_and_b64 s[24:25], s[4:5], exec
	s_cselect_b32 s55, s57, s17
	s_cselect_b32 s83, s56, s16
	s_ashr_i32 s53, s52, 31
	s_lshl_b64 s[24:25], s[52:53], 21
	s_add_u32 s62, s97, s24
	s_addc_u32 s63, s72, s25
	s_and_b64 s[24:25], s[4:5], exec
	s_cselect_b32 s53, s63, s3
	s_cselect_b32 s84, s62, s2
	s_add_u32 s85, s2, 0x100
	v_mov_b32_e32 v2, 0
	s_addc_u32 s86, s3, 0
	s_mov_b32 s87, -2
	s_waitcnt lgkmcnt(0)
	v_mov_b32_e32 v3, v2
	v_mov_b32_e32 v4, v2
	v_mov_b32_e32 v5, v2
	v_mov_b32_e32 v6, v2
	v_mov_b32_e32 v7, v2
	v_mov_b32_e32 v8, v2
	v_mov_b32_e32 v9, v2
	v_mov_b32_e32 v18, v2
	v_mov_b32_e32 v19, v2
	v_mov_b32_e32 v20, v2
	v_mov_b32_e32 v21, v2
	v_mov_b32_e32 v22, v2
	v_mov_b32_e32 v23, v2
	v_mov_b32_e32 v24, v2
	v_mov_b32_e32 v25, v2
	v_mov_b32_e32 v34, v2
	v_mov_b32_e32 v35, v2
	v_mov_b32_e32 v36, v2
	v_mov_b32_e32 v37, v2
	v_mov_b32_e32 v38, v2
	v_mov_b32_e32 v39, v2
	v_mov_b32_e32 v40, v2
	v_mov_b32_e32 v41, v2
	v_mov_b32_e32 v50, v2
	v_mov_b32_e32 v51, v2
	v_mov_b32_e32 v52, v2
	v_mov_b32_e32 v53, v2
	v_mov_b32_e32 v54, v2
	v_mov_b32_e32 v55, v2
	v_mov_b32_e32 v56, v2
	v_mov_b32_e32 v57, v2
	v_mov_b32_e32 v10, v2
	v_mov_b32_e32 v11, v2
	v_mov_b32_e32 v12, v2
	v_mov_b32_e32 v13, v2
	v_mov_b32_e32 v14, v2
	v_mov_b32_e32 v15, v2
	v_mov_b32_e32 v16, v2
	v_mov_b32_e32 v17, v2
	v_mov_b32_e32 v26, v2
	v_mov_b32_e32 v27, v2
	v_mov_b32_e32 v28, v2
	v_mov_b32_e32 v29, v2
	v_mov_b32_e32 v30, v2
	v_mov_b32_e32 v31, v2
	v_mov_b32_e32 v32, v2
	v_mov_b32_e32 v33, v2
	v_mov_b32_e32 v42, v2
	v_mov_b32_e32 v43, v2
	v_mov_b32_e32 v44, v2
	v_mov_b32_e32 v45, v2
	v_mov_b32_e32 v46, v2
	v_mov_b32_e32 v47, v2
	v_mov_b32_e32 v48, v2
	v_mov_b32_e32 v49, v2
	v_mov_b32_e32 v58, v2
	v_mov_b32_e32 v59, v2
	v_mov_b32_e32 v60, v2
	v_mov_b32_e32 v61, v2
	v_mov_b32_e32 v62, v2
	v_mov_b32_e32 v63, v2
	v_mov_b32_e32 v64, v2
	v_mov_b32_e32 v65, v2
	v_mov_b32_e32 v66, v2
	v_mov_b32_e32 v67, v2
	v_mov_b32_e32 v68, v2
	v_mov_b32_e32 v69, v2
	v_mov_b32_e32 v70, v2
	v_mov_b32_e32 v71, v2
	v_mov_b32_e32 v72, v2
	v_mov_b32_e32 v73, v2
	v_mov_b32_e32 v82, v2
	v_mov_b32_e32 v83, v2
	v_mov_b32_e32 v84, v2
	v_mov_b32_e32 v85, v2
	v_mov_b32_e32 v86, v2
	v_mov_b32_e32 v87, v2
	v_mov_b32_e32 v88, v2
	v_mov_b32_e32 v89, v2
	v_mov_b32_e32 v98, v2
	v_mov_b32_e32 v99, v2
	v_mov_b32_e32 v100, v2
	v_mov_b32_e32 v101, v2
	v_mov_b32_e32 v102, v2
	v_mov_b32_e32 v103, v2
	v_mov_b32_e32 v104, v2
	v_mov_b32_e32 v105, v2
	v_mov_b32_e32 v114, v2
	v_mov_b32_e32 v115, v2
	v_mov_b32_e32 v116, v2
	v_mov_b32_e32 v117, v2
	v_mov_b32_e32 v118, v2
	v_mov_b32_e32 v119, v2
	v_mov_b32_e32 v120, v2
	v_mov_b32_e32 v121, v2
	v_mov_b32_e32 v74, v2
	v_mov_b32_e32 v75, v2
	v_mov_b32_e32 v76, v2
	v_mov_b32_e32 v77, v2
	v_mov_b32_e32 v78, v2
	v_mov_b32_e32 v79, v2
	v_mov_b32_e32 v80, v2
	v_mov_b32_e32 v81, v2
	v_mov_b32_e32 v90, v2
	v_mov_b32_e32 v91, v2
	v_mov_b32_e32 v92, v2
	v_mov_b32_e32 v93, v2
	v_mov_b32_e32 v94, v2
	v_mov_b32_e32 v95, v2
	v_mov_b32_e32 v96, v2
	v_mov_b32_e32 v97, v2
	v_mov_b32_e32 v106, v2
	v_mov_b32_e32 v107, v2
	v_mov_b32_e32 v108, v2
	v_mov_b32_e32 v109, v2
	v_mov_b32_e32 v110, v2
	v_mov_b32_e32 v111, v2
	v_mov_b32_e32 v112, v2
	v_mov_b32_e32 v113, v2
	v_mov_b32_e32 v122, v2
	v_mov_b32_e32 v123, v2
	v_mov_b32_e32 v124, v2
	v_mov_b32_e32 v125, v2
	v_mov_b32_e32 v126, v2
	v_mov_b32_e32 v127, v2
	v_mov_b32_e32 v128, v2
	v_mov_b32_e32 v129, v2
	s_nop 0
	s_nop 0
	s_nop 0
	s_nop 0
	s_nop 0
	s_nop 0
	s_nop 0
	s_nop 0
	s_nop 0
	s_nop 0
	s_nop 0
	s_nop 0
	s_nop 0

;     __device__ bool next(int i, Unit& u) const { if (i > 1) return false; const int xcd = c & 7, idx = c >> 3; u.pm = 16 * i + 4 * (xcd >> 1) + (idx & 3); u.pn = 8 * (xcd & 1) + (idx >> 2); return true; }
; #define PG8_STAGE(bufoff, gbase, voff) do { const char* _gb = (const char*)(gbase); asm volatile("" : "+s"(_gb)); _Pragma("unroll") for (int _i = 0; _i < 2; ++_i) { asm volatile("" : "+v"((voff)[_i])); \
;         __builtin_amdgcn_global_load_lds((const unsigned*)(_gb + (voff)[_i]), (PG8_LAS unsigned*)(lds + (bufoff) + ldsw + _i * 8192), 16, 0, 0); } } while (0)
; #define PG8_LDA(dst, b, h) do { _Pragma("unroll") for (int m = 0; m < 4; ++m) _Pragma("unroll") for (int k = 0; k < 2; ++k) dst[m][k] = *(const PG8_LAS bf16x8*)(lds + PG8_SA(b, h) + aoff + m * 2048 + k * 1024); } while (0)
; #define PG8_LDB(dst, b, h) do { _Pragma("unroll") for (int n = 0; n < 2; ++n) _Pragma("unroll") for (int k = 0; k < 2; ++k) dst[n][k] = *(const PG8_LAS bf16x8*)(lds + PG8_SB(b, h) + boff + n * 2048 + k * 1024); } while (0)
; #define PG8_SCHED __builtin_amdgcn_sched_barrier(0)
; template <class Epi, class Sched, bool ALIGN_EPI = false, bool SP2 = false>
; __device__ __forceinline__ void gemm_phase(PG8_LAS unsigned char* lds, const Gemm g, const Sched& S, const Epi& E) {
;     ...
;         const bool has_next = S.next(ui + 1, nxt);
;         const char* nA = has_next ? (const char*)g.A + (size_t)nxt.pm * tstep : cA; const char* nB = has_next ? (const char*)g.Bt + (size_t)nxt.pn * tstep : cB;
;         for (int t = 0; t < nt; t += 2) {
;             const bool last = (t == nt - 2);
;             const char* a1 = cA + (size_t)(t + 1) * kstep;
;             const char* a2 = last ? nA : cA + (size_t)(t + 2) * kstep; const char* b2 = last ? nB : cB + (size_t)(t + 2) * kstep;
;             const char* a3 = a2 + kstep; const char* b3 = b2 + kstep;
;             if (last && has_next) S.a_ready(nxt);
;             if constexpr (SP2) {
;             PG8_LDB(B0, 0, 0); PG8_LDB(B1, 0, 1); PG8_SCHED; PG8_LDA(At, 0, 0); PG8_STAGE(PG8_SA(1, 1), a1 + hstep, voffA);
;     ...
; #pragma unroll
;         for (int a = 0; a < 2; ++a)
; #pragma unroll
;             for (int b = 0; b < 2; ++b)
; #pragma unroll
;                 for (int m = 0; m < 4; ++m)
; #pragma unroll
;                     for (int n = 0; n < 2; ++n) acc[a][b][m][n] = (f32x4){0.f, 0.f, 0.f, 0.f};
;         cur = nxt; cA = nA; cB = nB; ++ui;
.LBB0_932:
	s_ashr_i32 s51, s50, 31
	s_lshl_b64 s[2:3], s[50:51], 21
	s_add_u32 s52, s26, s2
	s_addc_u32 s53, s27, s3
	s_and_b64 s[2:3], s[10:11], exec
	s_cselect_b32 s20, s53, s13
	s_cselect_b32 s21, s52, s12
	s_ashr_i32 s49, s48, 31
	s_lshl_b64 s[2:3], s[48:49], 21
	s_add_u32 s54, s28, s2
	s_addc_u32 s55, s29, s3
	s_and_b64 s[2:3], s[10:11], exec
	s_cselect_b32 s49, s55, s15
	s_cselect_b32 s51, s54, s14
	s_add_u32 s62, s14, 0x100
	v_mov_b32_e32 v38, 0
	s_addc_u32 s63, s15, 0
	s_mov_b32 s83, -2
	v_mov_b32_e32 v39, v38
	v_mov_b32_e32 v40, v38
	v_mov_b32_e32 v41, v38
	v_mov_b32_e32 v42, v38
	v_mov_b32_e32 v43, v38
	v_mov_b32_e32 v44, v38
	v_mov_b32_e32 v45, v38
	v_mov_b32_e32 v46, v38
	v_mov_b32_e32 v47, v38
	v_mov_b32_e32 v48, v38
	v_mov_b32_e32 v49, v38
	v_mov_b32_e32 v54, v38
	v_mov_b32_e32 v55, v38
	v_mov_b32_e32 v56, v38
	v_mov_b32_e32 v57, v38
	v_mov_b32_e32 v2, v38
	v_mov_b32_e32 v3, v38
	v_mov_b32_e32 v4, v38
	v_mov_b32_e32 v5, v38
	v_mov_b32_e32 v10, v38
	v_mov_b32_e32 v11, v38
	v_mov_b32_e32 v12, v38
	v_mov_b32_e32 v13, v38
	v_mov_b32_e32 v14, v38
	v_mov_b32_e32 v15, v38
	v_mov_b32_e32 v16, v38
	v_mov_b32_e32 v17, v38
	v_mov_b32_e32 v18, v38
	v_mov_b32_e32 v19, v38
	v_mov_b32_e32 v20, v38
	v_mov_b32_e32 v21, v38
	v_mov_b32_e32 v50, v38
	v_mov_b32_e32 v51, v38
	v_mov_b32_e32 v52, v38
	v_mov_b32_e32 v53, v38
	v_mov_b32_e32 v58, v38
	v_mov_b32_e32 v59, v38
	v_mov_b32_e32 v60, v38
	v_mov_b32_e32 v61, v38
	v_mov_b32_e32 v66, v38
	v_mov_b32_e32 v67, v38
	v_mov_b32_e32 v68, v38
	v_mov_b32_e32 v69, v38
	v_mov_b32_e32 v70, v38
	v_mov_b32_e32 v71, v38
	v_mov_b32_e32 v72, v38
	v_mov_b32_e32 v73, v38
	v_mov_b32_e32 v22, v38
	v_mov_b32_e32 v23, v38
	v_mov_b32_e32 v24, v38
	v_mov_b32_e32 v25, v38
	v_mov_b32_e32 v26, v38
	v_mov_b32_e32 v27, v38
	v_mov_b32_e32 v28, v38
	v_mov_b32_e32 v29, v38
	v_mov_b32_e32 v30, v38
	v_mov_b32_e32 v31, v38
	v_mov_b32_e32 v32, v38
	v_mov_b32_e32 v33, v38
	v_mov_b32_e32 v34, v38
	v_mov_b32_e32 v35, v38
	v_mov_b32_e32 v36, v38
	v_mov_b32_e32 v37, v38
	v_mov_b32_e32 v102, v38
	v_mov_b32_e32 v103, v38
	v_mov_b32_e32 v104, v38
	v_mov_b32_e32 v105, v38
	v_mov_b32_e32 v122, v38
	v_mov_b32_e32 v123, v38
	v_mov_b32_e32 v124, v38
	v_mov_b32_e32 v125, v38
	v_mov_b32_e32 v98, v38
	v_mov_b32_e32 v99, v38
	v_mov_b32_e32 v100, v38
	v_mov_b32_e32 v101, v38
	v_mov_b32_e32 v126, v38
	v_mov_b32_e32 v127, v38
	v_mov_b32_e32 v128, v38
	v_mov_b32_e32 v129, v38
	v_mov_b32_e32 v74, v38
	v_mov_b32_e32 v75, v38
	v_mov_b32_e32 v76, v38
	v_mov_b32_e32 v77, v38
	v_mov_b32_e32 v78, v38
	v_mov_b32_e32 v79, v38
	v_mov_b32_e32 v80, v38
	v_mov_b32_e32 v81, v38
	v_mov_b32_e32 v82, v38
	v_mov_b32_e32 v83, v38
	v_mov_b32_e32 v84, v38
	v_mov_b32_e32 v85, v38
	v_mov_b32_e32 v94, v38
	v_mov_b32_e32 v95, v38
	v_mov_b32_e32 v96, v38
	v_mov_b32_e32 v97, v38
	v_mov_b32_e32 v110, v38
	v_mov_b32_e32 v111, v38
	v_mov_b32_e32 v112, v38
	v_mov_b32_e32 v113, v38
	v_mov_b32_e32 v130, v38
	v_mov_b32_e32 v131, v38
	v_mov_b32_e32 v132, v38
	v_mov_b32_e32 v133, v38
	v_mov_b32_e32 v90, v38
	v_mov_b32_e32 v91, v38
	v_mov_b32_e32 v92, v38
	v_mov_b32_e32 v93, v38
	v_mov_b32_e32 v134, v38
	v_mov_b32_e32 v135, v38
	v_mov_b32_e32 v136, v38
	v_mov_b32_e32 v137, v38
	v_mov_b32_e32 v86, v38
	v_mov_b32_e32 v87, v38
	v_mov_b32_e32 v88, v38
	v_mov_b32_e32 v89, v38
	v_mov_b32_e32 v106, v38
	v_mov_b32_e32 v107, v38
	v_mov_b32_e32 v108, v38
	v_mov_b32_e32 v109, v38
	v_mov_b32_e32 v114, v38
	v_mov_b32_e32 v115, v38
	v_mov_b32_e32 v116, v38
	v_mov_b32_e32 v117, v38
	v_mov_b32_e32 v118, v38
	v_mov_b32_e32 v119, v38
	v_mov_b32_e32 v120, v38
	v_mov_b32_e32 v121, v38
	s_nop 0
	s_nop 0
	s_nop 0
	s_nop 0
	s_nop 0
	s_nop 0
	s_nop 0

;     __device__ bool next(int i, Unit& u) const { if (i > 1) return false; const int xcd = c & 7, idx = c >> 3; u.pm = 16 * i + 4 * (xcd >> 1) + (idx & 3); u.pn = 8 * (xcd & 1) + (idx >> 2); return true; }
; #define PG8_STAGE(bufoff, gbase, voff) do { const char* _gb = (const char*)(gbase); asm volatile("" : "+s"(_gb)); _Pragma("unroll") for (int _i = 0; _i < 2; ++_i) { asm volatile("" : "+v"((voff)[_i])); \
;         __builtin_amdgcn_global_load_lds((const unsigned*)(_gb + (voff)[_i]), (PG8_LAS unsigned*)(lds + (bufoff) + ldsw + _i * 8192), 16, 0, 0); } } while (0)
; #define PG8_LDA(dst, b, h) do { _Pragma("unroll") for (int m = 0; m < 4; ++m) _Pragma("unroll") for (int k = 0; k < 2; ++k) dst[m][k] = *(const PG8_LAS bf16x8*)(lds + PG8_SA(b, h) + aoff + m * 2048 + k * 1024); } while (0)
; #define PG8_LDB(dst, b, h) do { _Pragma("unroll") for (int n = 0; n < 2; ++n) _Pragma("unroll") for (int k = 0; k < 2; ++k) dst[n][k] = *(const PG8_LAS bf16x8*)(lds + PG8_SB(b, h) + boff + n * 2048 + k * 1024); } while (0)
; #define PG8_SCHED __builtin_amdgcn_sched_barrier(0)
; template <class Epi, class Sched, bool ALIGN_EPI = false, bool SP2 = false>
; __device__ __forceinline__ void gemm_phase(PG8_LAS unsigned char* lds, const Gemm g, const Sched& S, const Epi& E) {
;     ...
;         const bool has_next = S.next(ui + 1, nxt);
;         const char* nA = has_next ? (const char*)g.A + (size_t)nxt.pm * tstep : cA; const char* nB = has_next ? (const char*)g.Bt + (size_t)nxt.pn * tstep : cB;
;         for (int t = 0; t < nt; t += 2) {
;             const bool last = (t == nt - 2);
;             const char* a1 = cA + (size_t)(t + 1) * kstep;
;             const char* a2 = last ? nA : cA + (size_t)(t + 2) * kstep; const char* b2 = last ? nB : cB + (size_t)(t + 2) * kstep;
;             const char* a3 = a2 + kstep; const char* b3 = b2 + kstep;
;             if (last && has_next) S.a_ready(nxt);
;             if constexpr (SP2) {
;             PG8_LDB(B0, 0, 0); PG8_LDB(B1, 0, 1); PG8_SCHED; PG8_LDA(At, 0, 0); PG8_STAGE(PG8_SA(1, 1), a1 + hstep, voffA);
;     ...
; #pragma unroll
;         for (int a = 0; a < 2; ++a)
; #pragma unroll
;             for (int b = 0; b < 2; ++b)
; #pragma unroll
;                 for (int m = 0; m < 4; ++m)
; #pragma unroll
;                     for (int n = 0; n < 2; ++n) acc[a][b][m][n] = (f32x4){0.f, 0.f, 0.f, 0.f};
;         cur = nxt; cA = nA; cB = nB; ++ui;
.LBB0_1216:
	s_mov_b32 s14, s55
	s_or_b32 s55, s28, s40
	s_mul_i32 s4, s55, 0x600000
	s_mov_b64 s[6:7], s[10:11]
	s_add_u32 s10, s33, s4
	s_addc_u32 s11, s38, 0
	s_and_b64 s[4:5], s[26:27], exec
	s_cselect_b32 s56, s11, s7
	s_cselect_b32 s57, s10, s6
	s_mov_b32 s58, -2
	s_mov_b64 s[4:5], s[20:21]
	v_mov_b32_e32 v0, 0
	v_mov_b32_e32 v1, v179
	v_mov_b32_e32 v2, v179
	v_mov_b32_e32 v3, v179
	v_mov_b32_e32 v4, 0
	v_mov_b32_e32 v5, v179
	v_mov_b32_e32 v6, v179
	v_mov_b32_e32 v7, v179
	v_mov_b32_e32 v16, 0
	v_mov_b32_e32 v17, v179
	v_mov_b32_e32 v18, v179
	v_mov_b32_e32 v19, v179
	v_mov_b32_e32 v20, 0
	v_mov_b32_e32 v21, v179
	v_mov_b32_e32 v22, v179
	v_mov_b32_e32 v23, v179
	v_mov_b32_e32 v32, 0
	v_mov_b32_e32 v33, v179
	v_mov_b32_e32 v34, v179
	v_mov_b32_e32 v35, v179
	v_mov_b32_e32 v36, 0
	v_mov_b32_e32 v37, v179
	v_mov_b32_e32 v38, v179
	v_mov_b32_e32 v39, v179
	v_mov_b32_e32 v48, 0
	v_mov_b32_e32 v49, v179
	v_mov_b32_e32 v50, v179
	v_mov_b32_e32 v51, v179
	v_mov_b32_e32 v52, 0
	v_mov_b32_e32 v53, v179
	v_mov_b32_e32 v54, v179
	v_mov_b32_e32 v55, v179
	v_mov_b32_e32 v8, 0
	v_mov_b32_e32 v9, v179
	v_mov_b32_e32 v10, v179
	v_mov_b32_e32 v11, v179
	v_mov_b32_e32 v12, 0
	v_mov_b32_e32 v13, v179
	v_mov_b32_e32 v14, v179
	v_mov_b32_e32 v15, v179
	v_mov_b32_e32 v24, 0
	v_mov_b32_e32 v25, v179
	v_mov_b32_e32 v26, v179
	v_mov_b32_e32 v27, v179
	v_mov_b32_e32 v28, 0
	v_mov_b32_e32 v29, v179
	v_mov_b32_e32 v30, v179
	v_mov_b32_e32 v31, v179
	v_mov_b32_e32 v40, 0
	v_mov_b32_e32 v41, v179
	v_mov_b32_e32 v42, v179
	v_mov_b32_e32 v43, v179
	v_mov_b32_e32 v44, 0
	v_mov_b32_e32 v45, v179
	v_mov_b32_e32 v46, v179
	v_mov_b32_e32 v47, v179
	v_mov_b32_e32 v56, 0
	v_mov_b32_e32 v57, v179
	v_mov_b32_e32 v58, v179
	v_mov_b32_e32 v59, v179
	v_mov_b32_e32 v60, 0
	v_mov_b32_e32 v61, v179
	v_mov_b32_e32 v62, v179
	v_mov_b32_e32 v63, v179
	v_mov_b32_e32 v64, 0
	v_mov_b32_e32 v65, v179
	v_mov_b32_e32 v66, v179
	v_mov_b32_e32 v67, v179
	v_mov_b32_e32 v68, 0
	v_mov_b32_e32 v69, v179
	v_mov_b32_e32 v70, v179
	v_mov_b32_e32 v71, v179
	v_mov_b32_e32 v80, 0
	v_mov_b32_e32 v81, v179
	v_mov_b32_e32 v82, v179
	v_mov_b32_e32 v83, v179
	v_mov_b32_e32 v84, 0
	v_mov_b32_e32 v85, v179
	v_mov_b32_e32 v86, v179
	v_mov_b32_e32 v87, v179
	v_mov_b32_e32 v96, 0
	v_mov_b32_e32 v97, v179
	v_mov_b32_e32 v98, v179
	v_mov_b32_e32 v99, v179
	v_mov_b32_e32 v100, 0
	v_mov_b32_e32 v101, v179
	v_mov_b32_e32 v102, v179
	v_mov_b32_e32 v103, v179
	v_mov_b32_e32 v112, 0
	v_mov_b32_e32 v113, v179
	v_mov_b32_e32 v114, v179
	v_mov_b32_e32 v115, v179
	v_mov_b32_e32 v116, 0
	v_mov_b32_e32 v117, v179
	v_mov_b32_e32 v118, v179
	v_mov_b32_e32 v119, v179
	v_mov_b32_e32 v72, 0
	v_mov_b32_e32 v73, v179
	v_mov_b32_e32 v74, v179
	v_mov_b32_e32 v75, v179
	v_mov_b32_e32 v76, 0
	v_mov_b32_e32 v77, v179
	v_mov_b32_e32 v78, v179
	v_mov_b32_e32 v79, v179
	v_mov_b32_e32 v88, 0
	v_mov_b32_e32 v89, v179
	v_mov_b32_e32 v90, v179
	v_mov_b32_e32 v91, v179
	v_mov_b32_e32 v92, 0
	v_mov_b32_e32 v93, v179
	v_mov_b32_e32 v94, v179
	v_mov_b32_e32 v95, v179
	v_mov_b32_e32 v104, 0
	v_mov_b32_e32 v105, v179
	v_mov_b32_e32 v106, v179
	v_mov_b32_e32 v107, v179
	v_mov_b32_e32 v108, 0
	v_mov_b32_e32 v109, v179
	v_mov_b32_e32 v110, v179
	v_mov_b32_e32 v111, v179
	v_mov_b32_e32 v120, 0
	v_mov_b32_e32 v121, v179
	v_mov_b32_e32 v122, v179
	v_mov_b32_e32 v123, v179
	v_mov_b32_e32 v124, 0
	v_mov_b32_e32 v125, v179
	v_mov_b32_e32 v126, v179
	v_mov_b32_e32 v127, v179
	s_nop 0
	s_nop 0
	s_nop 0
	s_nop 0
	s_nop 0
	s_nop 0
	s_nop 0
	s_nop 0
	s_nop 0
	s_nop 0
	s_nop 0
	s_nop 0
	s_nop 0
	s_nop 0
